# cross-row lane exchanges (mLSTM ssq, attention rope/softmax, post-norm sums) via v_permlane16/32_swap instead of ds_bpermute
# baseline (speedup 1.0000x reference)
; __device__ __forceinline__ float bflo(unsigned w) { return __uint_as_float(w << 16); }
; __device__ __forceinline__ float bfhi(unsigned w) { return __uint_as_float(w & 0xffff0000u); }
; __device__ __forceinline__ unsigned cvt_pk_bf16(float lo, float hi) { const f32x2_t f = {lo, hi}; const bf16x2_t b = __builtin_convertvector(f, bf16x2_t); return __builtin_bit_cast(unsigned, b); }
; __device__ __forceinline__ float sigmoidf_(float x) { return __builtin_amdgcn_rcpf(1.0f + __expf(-x)); }
; __device__ __forceinline__ float siluf_(float x) { return x * sigmoidf_(x); }
; __device__ __forceinline__ void p2_mlstm(const Params& p, LAS unsigned char* lds) {
;     ...
;                 const float den = __shfl(hacc[2][0], r);
;                 const float dn = fmaxf(fabsf(den), __expf(-(PB[gl0 + l] + mml)));
;                 const float rdn = 1.0f / dn;
;                 const int t = tok0 + l;
;                 float ssq = 0.f;
; #pragma unroll
;                 for (int vt = 0; vt < 2; ++vt) {
;                     const int c = h * 256 + sl * 32 + 16 * vt + 4 * q;
;                     const u32x2 ow = owr[vt], zw = zwr[vt];
;                     const float4 nw = *(const float4*)(p.m_norm_w + c);
;                     const float og[4] = {bflo(ow.x), bfhi(ow.x), bflo(ow.y), bfhi(ow.y)};
;                     const float zg[4] = {bflo(zw.x), bfhi(zw.x), bflo(zw.y), bfhi(zw.y)};
;                     const float nwv[4] = {nw.x, nw.y, nw.z, nw.w};
;                     float uo[4];
; #pragma unroll
;                     for (int j = 0; j < 4; ++j) { const float hs = hacc[vt][j] * rdn * sigmoidf_(og[j]); ssq += hs * hs; uo[j] = hs * nwv[j] * siluf_(zg[j]); }
;                     u32x2 w; w.x = cvt_pk_bf16(uo[0], uo[1]); w.y = cvt_pk_bf16(uo[2], uo[3]);
;                     stg8(HM + (size_t)tok0 * 1024, hoff + 32u * vt, w);
;                 }
;                 ssq += __shfl_xor(ssq, 16); ssq += __shfl_xor(ssq, 32);
;                 if (q == 0) SSQ[((size_t)t * 4 + h) * 8 + sl] = ssq;
.Lml_noq:
	v_lshlrev_b32_e32 v114, 16, v186
	v_and_b32_e32 v115, 0xffff0000, v186
	v_lshlrev_b32_e32 v118, 16, v189
	s_waitcnt lgkmcnt(1)
	v_add_f32_e32 v6, v251, v6
	v_mul_f32_e32 v6, 0xbfb8aa3b, v6
	v_exp_f32_e32 v6, v6
	s_waitcnt lgkmcnt(0)
	v_max_f32_e64 v5, |v5|, |v5|
	v_and_b32_e32 v119, 0xffff0000, v189
	v_max_f32_e32 v5, v5, v6
	v_div_scale_f32 v6, s[0:1], v5, v5, 1.0
	v_rcp_f32_e32 v7, v6
	s_nop 0
	v_fma_f32 v108, -v6, v7, 1.0
	v_fmac_f32_e32 v7, v108, v7
	v_div_scale_f32 v108, vcc, 1.0, v5, 1.0
	v_mul_f32_e32 v109, v108, v7
	v_fma_f32 v110, -v6, v109, v108
	v_fmac_f32_e32 v109, v110, v7
	v_fma_f32 v6, -v6, v109, v108
	v_div_fmas_f32 v6, v6, v7, v109
	v_div_fixup_f32 v6, v6, v5, 1.0
	v_lshlrev_b32_e32 v5, 16, v188
	v_mul_f32_e32 v5, 0xbfb8aa3b, v5
	v_exp_f32_e32 v5, v5
	v_and_b32_e32 v7, 0xffff0000, v188
	v_pk_mul_f32 v[104:105], v[104:105], v[6:7] op_sel_hi:[1,0]
	v_pk_mul_f32 v[106:107], v[106:107], v[6:7] op_sel_hi:[1,0]
	v_add_f32_e32 v5, 1.0, v5
	v_rcp_f32_e32 v112, v5
	v_mul_f32_e32 v5, 0xbfb8aa3b, v7
	v_exp_f32_e32 v5, v5
	v_and_b32_e32 v7, 0xffff0000, v184
	v_pk_mul_f32 v[100:101], v[100:101], v[6:7] op_sel_hi:[1,0]
	v_add_f32_e32 v5, 1.0, v5
	v_rcp_f32_e32 v113, v5
	v_mul_f32_e32 v5, 0xbfb8aa3b, v114
	v_exp_f32_e32 v5, v5
	v_pk_mul_f32 v[112:113], v[112:113], v[104:105]
	s_nop 0
	v_pk_mul_f32 v[104:105], v[112:113], v[112:113]
	v_add_f32_e32 v5, 1.0, v5
	v_rcp_f32_e32 v116, v5
	v_mul_f32_e32 v5, 0xbfb8aa3b, v115
	v_exp_f32_e32 v5, v5
	v_pk_mul_f32 v[108:109], v[120:121], v[112:113]
	v_add_f32_e32 v5, 1.0, v5
	v_rcp_f32_e32 v117, v5
	v_mul_f32_e32 v5, 0xbfb8aa3b, v118
	v_exp_f32_e32 v5, v5
	v_lshlrev_b32_e32 v118, 16, v185
	v_pk_mul_f32 v[112:113], v[116:117], v[114:115]
	v_lshlrev_b32_e32 v114, 16, v187
	v_add_f32_e32 v5, 1.0, v5
	v_pk_mul_f32 v[108:109], v[112:113], v[108:109]
	v_rcp_f32_e32 v112, v5
	v_mul_f32_e32 v5, 0xbfb8aa3b, v119
	v_exp_f32_e32 v5, v5
	v_and_b32_e32 v115, 0xffff0000, v187
	v_cvt_pk_bf16_f32 v108, v108, v109
	v_and_b32_e32 v119, 0xffff0000, v185
	v_add_f32_e32 v5, 1.0, v5
	v_rcp_f32_e32 v113, v5
	v_mul_f32_e32 v5, 0xbfb8aa3b, v114
	v_exp_f32_e32 v5, v5
	v_pk_mul_f32 v[112:113], v[112:113], v[106:107]
	s_nop 0
	v_pk_mul_f32 v[106:107], v[112:113], v[112:113]
	v_add_f32_e32 v5, 1.0, v5
	v_rcp_f32_e32 v116, v5
	v_mul_f32_e32 v5, 0xbfb8aa3b, v115
	v_exp_f32_e32 v5, v5
	v_pk_mul_f32 v[110:111], v[122:123], v[112:113]
	v_add_f32_e32 v5, 1.0, v5
	v_rcp_f32_e32 v117, v5
	v_lshlrev_b32_e32 v5, 16, v184
	v_mul_f32_e32 v5, 0xbfb8aa3b, v5
	v_exp_f32_e32 v5, v5
	v_pk_mul_f32 v[112:113], v[116:117], v[114:115]
	v_lshlrev_b32_e32 v114, 16, v182
	v_pk_mul_f32 v[110:111], v[112:113], v[110:111]
	v_add_f32_e32 v5, 1.0, v5
	v_cvt_pk_bf16_f32 v109, v110, v111
	global_store_dwordx2 v[174:175], v[108:109], off
	v_rcp_f32_e32 v112, v5
	v_mul_f32_e32 v5, 0xbfb8aa3b, v7
	v_exp_f32_e32 v5, v5
	v_and_b32_e32 v115, 0xffff0000, v182
	v_pk_mul_f32 v[6:7], v[102:103], v[6:7] op_sel_hi:[1,0]
	v_add_f32_e32 v5, 1.0, v5
	v_rcp_f32_e32 v113, v5
	v_mul_f32_e32 v5, 0xbfb8aa3b, v114
	v_exp_f32_e32 v5, v5
	v_pk_mul_f32 v[100:101], v[112:113], v[100:101]
	s_nop 0
	v_pk_mul_f32 v[112:113], v[100:101], v[100:101]
	v_add_f32_e32 v5, 1.0, v5
	v_rcp_f32_e32 v116, v5
	v_mul_f32_e32 v5, 0xbfb8aa3b, v115
	v_exp_f32_e32 v5, v5
	v_pk_mul_f32 v[100:101], v[124:125], v[100:101]
	v_add_f32_e32 v5, 1.0, v5
	v_rcp_f32_e32 v117, v5
	v_mul_f32_e32 v5, 0xbfb8aa3b, v118
	v_exp_f32_e32 v5, v5
	v_pk_mul_f32 v[108:109], v[116:117], v[114:115]
	s_nop 0
	v_pk_mul_f32 v[100:101], v[108:109], v[100:101]
	v_add_f32_e32 v5, 1.0, v5
	v_rcp_f32_e32 v108, v5
	v_mul_f32_e32 v5, 0xbfb8aa3b, v119
	v_exp_f32_e32 v5, v5
	v_lshlrev_b32_e32 v114, 16, v183
	v_and_b32_e32 v115, 0xffff0000, v183
	v_cvt_pk_bf16_f32 v100, v100, v101
	v_add_f32_e32 v5, 1.0, v5
	v_rcp_f32_e32 v109, v5
	v_mul_f32_e32 v5, 0xbfb8aa3b, v114
	v_exp_f32_e32 v5, v5
	v_pk_mul_f32 v[6:7], v[108:109], v[6:7]
	s_nop 0
	v_pk_mul_f32 v[102:103], v[6:7], v[6:7]
	v_add_f32_e32 v5, 1.0, v5
	v_rcp_f32_e32 v108, v5
	v_add_f32_e32 v5, v104, v105
	v_add_f32_e32 v5, v106, v5
	v_add_f32_e32 v5, v107, v5
	v_add_f32_e32 v5, v112, v5
	v_add_f32_e32 v5, v113, v5
	v_add_f32_e32 v5, v102, v5
	v_mul_f32_e32 v102, 0xbfb8aa3b, v115
	v_exp_f32_e32 v102, v102
	v_add_f32_e32 v5, v103, v5
	v_pk_mul_f32 v[6:7], v[6:7], v[126:127]
	v_add_f32_e32 v102, 1.0, v102
	v_rcp_f32_e32 v109, v102
	s_nop 0
	v_pk_mul_f32 v[102:103], v[108:109], v[114:115]
	s_nop 0
	v_pk_mul_f32 v[6:7], v[102:103], v[6:7]
	s_nop 0
	v_cvt_pk_bf16_f32 v101, v6, v7
	v_mov_b32_e32 v6, v5
	global_store_dwordx2 v[174:175], v[100:101], off offset:32
	s_waitcnt lgkmcnt(0)
	s_nop 0
	v_permlane16_swap_b32 v5, v6
	s_nop 1
	v_add_f32_e32 v5, v5, v6
	v_mov_b32_e32 v6, v5
	s_nop 1
	v_permlane32_swap_b32 v5, v6
	s_nop 1
	s_and_saveexec_b64 s[0:1], s[12:13]
	s_cbranch_execz .LBB0_345
	s_waitcnt lgkmcnt(0)
	v_add_f32_e32 v5, v5, v6
	v_add_u32_e32 v6, s80, v202
	v_add_u32_e32 v6, 0xffffff80, v6
	v_ashrrev_i32_e32 v7, 31, v6
	v_lshlrev_b64 v[6:7], 7, v[6:7]
	v_lshl_add_u64 v[6:7], s[78:79], 0, v[6:7]
	global_store_dword v[6:7], v5, off

; #define LAS __attribute__((address_space(3)))
; __device__ __forceinline__ void p4_attn(const Params& p, LAS unsigned char* lds, const int dummy) {
;     ...
;             *(LAS u32x4*)(KA + row * KA_STRIDE + (8 * pv) * 2) = o1;
;             *(LAS u32x4*)(KA + row * KA_STRIDE + (16 + 8 * pv) * 2) = o2;
; #pragma unroll
;             for (int i = 0; i < 6; ++i) { const int task = tid + 512 * i; const int row2 = task / 12, v = 4 + task % 12; *(LAS u32x4*)(KA + row2 * KA_STRIDE + v * 16) = kr[2 + i]; }
; #pragma unroll
;             for (int vi = 0; vi < 8; ++vi) *(LAS u32x4*)(VB + row * VB_STRIDE + (pv * 64 + vi * 8) * 2) = vr[vi];
;         }
;         const int ql = 16 * wid + r; const int jq = blk * 128 + ql; const int posq = jq * dil + rr; const size_t tq = (size_t)(tokb + posq);
;         bf16x8 qf[4];
;         {
;             bf16_t* qsrc = R1 + tq * QZ_LD + qcol;
; #pragma unroll
;             for (int kk = 0; kk < 4; ++kk) {
;                 const u32x4 av = *(const u32x4*)(qsrc + 32 * kk + 8 * q);
;                 float x[8]; unpack8(av, x);
;                 if (kk == 0) {
;                     const int fi = 8 * (q & 1);
;                     const float4 ca = *(const float4*)(RC + posq * 16 + fi), cb = *(const float4*)(RC + posq * 16 + fi + 4);
;                     const float4 sa = *(const float4*)(RS + posq * 16 + fi), sb = *(const float4*)(RS + posq * 16 + fi + 4);
;                     const float cc[8] = {ca.x, ca.y, ca.z, ca.w, cb.x, cb.y, cb.z, cb.w}, sn[8] = {sa.x, sa.y, sa.z, sa.w, sb.x, sb.y, sb.z, sb.w};
; #pragma unroll
;                     for (int e = 0; e < 8; ++e) { const float xo = __shfl_xor(x[e], 32); x[e] = (q < 2) ? (x[e] * cc[e] - xo * sn[e]) : (x[e] * cc[e] + xo * sn[e]); }
.LBB0_594:
	s_or_b64 exec, exec, s[0:1]
	s_mul_hi_i32 s0, s8, 0x2aaaaaab
	v_add_u32_e32 v37, s11, v145
	s_lshr_b32 s1, s0, 31
	s_lshr_b32 s0, s0, 5
	v_lshlrev_b32_e32 v37, s4, v37
	s_add_i32 s1, s0, s1
	v_add_u32_e32 v37, s5, v37
	s_bfe_u32 s10, s8, 0x20004
	v_lshl_add_u32 v124, s1, 11, v37
	s_lshl_b32 s0, s9, 9
	s_lshl_b32 s6, s10, 7
	v_ashrrev_i32_e32 v125, 31, v124
	v_readlane_b32 s4, v254, 20
	s_or_b32 s0, s0, s6
	v_lshlrev_b64 v[38:39], 12, v[124:125]
	v_readlane_b32 s5, v254, 21
	s_ashr_i32 s1, s0, 31
	v_mov_b32_e32 v121, v36
	v_lshl_add_u64 v[38:39], s[4:5], 0, v[38:39]
	v_lshl_add_u64 v[126:127], s[0:1], 1, v[38:39]
	v_lshlrev_b32_e32 v68, 4, v37
	v_mov_b32_e32 v69, v36
	v_lshl_add_u64 v[38:39], v[126:127], 0, v[120:121]
	v_lshlrev_b64 v[68:69], 2, v[68:69]
	global_load_dwordx4 v[108:111], v[38:39], off
	v_lshl_add_u64 v[70:71], v[118:119], 0, v[68:69]
	v_lshl_add_u64 v[68:69], v[116:117], 0, v[68:69]
	global_load_dwordx4 v[80:83], v[68:69], off offset:16
	global_load_dwordx4 v[88:91], v[68:69], off
	global_load_dwordx4 v[84:87], v[70:71], off offset:16
	global_load_dwordx4 v[92:95], v[70:71], off
	global_load_dwordx4 v[76:79], v[38:39], off offset:64
	global_load_dwordx4 v[72:75], v[38:39], off offset:128
	s_nop 0
	global_load_dwordx4 v[68:71], v[38:39], off offset:192
	ds_write_b128 v172, v[96:99]
	ds_write_b128 v172, v[100:103] offset:32
	ds_write_b128 v173, v[8:11] offset:64
	ds_write_b128 v174, v[12:15] offset:64
	ds_write_b128 v175, v[16:19] offset:64
	ds_write_b128 v176, v[24:27] offset:64
	ds_write_b128 v177, v[28:31] offset:64
	ds_write_b128 v178, v[32:35] offset:64
	ds_write_b128 v179, v[20:23]
	ds_write_b128 v179, v[40:43] offset:9216
	ds_write_b128 v179, v[48:51] offset:18432
	ds_write_b128 v179, v[44:47] offset:27648
	ds_write_b128 v179, v[52:55] offset:36864
	ds_write_b128 v179, v[56:59] offset:46080
	ds_write_b128 v179, v[64:67] offset:55296
	ds_write_b128 v179, v[60:63] offset:64512
	v_readlane_b32 s0, v254, 51
	s_add_i32 s8, s8, s0
	s_cmpk_gt_i32 s8, 0x5ff
	s_cselect_b64 s[86:87], -1, 0
	s_and_b64 vcc, exec, s[86:87]
	v_readlane_b32 s1, v254, 52
	s_waitcnt lgkmcnt(0)
	s_barrier
	s_waitcnt vmcnt(7)
	v_lshlrev_b32_e32 v106, 16, v108
	v_and_b32_e32 v107, 0xffff0000, v108
	v_lshlrev_b32_e32 v102, 16, v109
	v_and_b32_e32 v103, 0xffff0000, v109
	v_lshlrev_b32_e32 v98, 16, v110
	v_and_b32_e32 v99, 0xffff0000, v110
	v_lshlrev_b32_e32 v96, 16, v111
	v_and_b32_e32 v97, 0xffff0000, v111
	v_mov_b32_e32 v110, v106
	v_mov_b32_e32 v111, v107
	v_mov_b32_e32 v108, v102
	v_mov_b32_e32 v109, v103
	v_mov_b32_e32 v104, v98
	v_mov_b32_e32 v105, v99
	v_mov_b32_e32 v100, v96
	v_mov_b32_e32 v101, v97
	s_nop 1
	v_permlane32_swap_b32 v110, v110
	v_permlane32_swap_b32 v111, v111
	v_permlane32_swap_b32 v108, v108
	v_permlane32_swap_b32 v109, v109
	v_permlane32_swap_b32 v104, v104
	v_permlane32_swap_b32 v105, v105
	v_permlane32_swap_b32 v100, v100
	v_permlane32_swap_b32 v101, v101
	s_nop 1

; #define LAS __attribute__((address_space(3)))
; __device__ __forceinline__ void p4_attn(const Params& p, LAS unsigned char* lds, const int dummy) {
;     ...
;         for (int gi = 0; gi < 3; ++gi) {
;             if (3 * gi + 2 >= ilo) {
;                 bf16x8 ka[3][4];
; #pragma unroll
;                 for (int i3 = 0; i3 < 3; ++i3)
; #pragma unroll
;                     for (int kk = 0; kk < 4; ++kk) ka[i3][kk] = *(const LAS bf16x8*)(KA + (16 * (wid + 3 * gi + i3) + r) * KA_STRIDE + (32 * kk + 8 * q) * 2);
;                 __builtin_amdgcn_sched_barrier(0);
; #pragma unroll
;                 for (int kk = 0; kk < 4; ++kk)
; #pragma unroll
;                     for (int i3 = 0; i3 < 3; ++i3) sT[3 * gi + i3] = __builtin_amdgcn_mfma_f32_16x16x32_bf16(ka[i3][kk], qf[kk], sT[3 * gi + i3], 0, 0, 0);
;                 __builtin_amdgcn_sched_barrier(0);
;             }
;         }
;         float mx = -1e30f;
; #pragma unroll
;         for (int i = 0; i < 9; ++i)
; #pragma unroll
;             for (int j = 0; j < 4; ++j) {
;                 const int kl = 16 * (wid + i) + 4 * q + j; const int dist = ql - kl + 128; const int jk = blk * 128 - 128 + kl;
;                 const bool valid = (dist >= 0) && (dist <= 128) && (jk >= 0);
;                 sT[i][j] = valid ? sT[i][j] : -1e30f; mx = fmaxf(mx, sT[i][j]);
;             }
;         mx = fmaxf(mx, __shfl_xor(mx, 16)); mx = fmaxf(mx, __shfl_xor(mx, 32));
.LBB0_618:
	ds_read_b128 v[68:71], v186
	ds_read_b128 v[202:205], v186 offset:64
	ds_read_b128 v[206:209], v186 offset:128
	ds_read_b128 v[214:217], v186 offset:192
	ds_read_b128 v[218:221], v187
	ds_read_b128 v[222:225], v187 offset:64
	ds_read_b128 v[226:229], v187 offset:128
	ds_read_b128 v[230:233], v187 offset:192
	ds_read_b128 v[234:237], v188
	ds_read_b128 v[238:241], v188 offset:64
	ds_read_b128 v[242:245], v188 offset:128
	ds_read_b128 v[246:249], v188 offset:192
	s_waitcnt lgkmcnt(11)
	v_mfma_f32_16x16x32_bf16 v[68:71], v[68:71], v[80:83], 0
	s_mov_b32 s81, s80
	s_mov_b32 s82, s80
	s_mov_b32 s83, s80
	s_waitcnt lgkmcnt(7)
	v_mfma_f32_16x16x32_bf16 v[218:221], v[218:221], v[80:83], 0
	s_waitcnt lgkmcnt(3)
	v_mfma_f32_16x16x32_bf16 v[80:83], v[234:237], v[80:83], 0
	v_mfma_f32_16x16x32_bf16 v[68:71], v[202:205], v[76:79], v[68:71]
	v_mfma_f32_16x16x32_bf16 v[202:205], v[222:225], v[76:79], v[218:221]
	s_waitcnt lgkmcnt(2)
	v_mfma_f32_16x16x32_bf16 v[76:79], v[238:241], v[76:79], v[80:83]
	v_mfma_f32_16x16x32_bf16 v[68:71], v[206:209], v[84:87], v[68:71]
	v_mfma_f32_16x16x32_bf16 v[80:83], v[226:229], v[84:87], v[202:205]
	s_waitcnt lgkmcnt(1)
	v_mfma_f32_16x16x32_bf16 v[76:79], v[242:245], v[84:87], v[76:79]
	v_mfma_f32_16x16x32_bf16 v[84:87], v[214:217], v[92:95], v[68:71]
	v_mfma_f32_16x16x32_bf16 v[80:83], v[230:233], v[92:95], v[80:83]
	s_nop 2
	v_mov_b64_e32 v[68:69], s[80:81]
	v_mov_b64_e32 v[70:71], s[82:83]
	s_waitcnt lgkmcnt(0)
	v_mfma_f32_16x16x32_bf16 v[76:79], v[246:249], v[92:95], v[76:79]
	s_sub_i32 s0, 0x7f, s11
	v_readlane_b32 s12, v254, 61
	v_cmp_lt_i32_e32 vcc, s0, v148
	v_readlane_b32 s13, v254, 62
	s_and_b64 vcc, s[12:13], vcc
	v_readlane_b32 s12, v254, 43
	v_cndmask_b32_e32 v37, v198, v96, vcc
	v_cmp_le_i32_e32 vcc, s0, v148
	v_readlane_b32 s13, v254, 44
	s_and_b64 vcc, s[12:13], vcc
	v_readlane_b32 s12, v254, 37
	v_cndmask_b32_e32 v39, v198, v97, vcc
	v_cmp_lt_i32_e32 vcc, s0, v149
	v_readlane_b32 s13, v254, 38
	s_and_b64 vcc, s[12:13], vcc
	v_readlane_b32 s12, v254, 39
	v_cndmask_b32_e32 v92, v198, v98, vcc
	v_cmp_lt_i32_e32 vcc, s0, v150
	v_readlane_b32 s13, v254, 40
	s_and_b64 vcc, s[12:13], vcc
	v_readlane_b32 s12, v254, 41
	v_cndmask_b32_e32 v93, v198, v99, vcc
	v_cmp_lt_i32_e32 vcc, s0, v151
	v_readlane_b32 s13, v254, 42
	s_and_b64 vcc, s[12:13], vcc
	v_readlane_b32 s12, v254, 47
	v_cndmask_b32_e32 v88, v198, v88, vcc
	v_cmp_le_i32_e32 vcc, s0, v151
	v_readlane_b32 s13, v254, 48
	s_and_b64 vcc, s[12:13], vcc
	v_readlane_b32 s12, v254, 49
	v_cndmask_b32_e32 v89, v198, v89, vcc
	v_cmp_lt_i32_e32 vcc, s0, v152
	v_readlane_b32 s13, v254, 50
	s_and_b64 vcc, s[12:13], vcc
	v_cndmask_b32_e32 v90, v198, v90, vcc
	v_cmp_lt_i32_e32 vcc, s0, v153
	s_and_b64 vcc, s[20:21], vcc
	s_mov_b32 s1, 0xf149f2ca
	v_cndmask_b32_e32 v91, v198, v91, vcc
	v_cmp_lt_i32_e32 vcc, s0, v154
	s_and_b64 vcc, s[22:23], vcc
	v_max3_f32 v38, v37, s1, v39
	v_cndmask_b32_e32 v72, v198, v72, vcc
	v_cmp_le_i32_e32 vcc, s0, v154
	s_and_b64 vcc, s[24:25], vcc
	v_max3_f32 v38, v38, v92, v93
	v_cndmask_b32_e32 v73, v198, v73, vcc
	v_cmp_lt_i32_e32 vcc, s0, v155
	s_and_b64 vcc, s[26:27], vcc
	v_max3_f32 v38, v38, v88, v89
	v_cndmask_b32_e32 v74, v198, v74, vcc
	v_cmp_lt_i32_e32 vcc, s0, v156
	s_and_b64 vcc, s[28:29], vcc
	v_max3_f32 v38, v38, v90, v91
	v_cndmask_b32_e32 v75, v198, v75, vcc
	v_cmp_lt_i32_e32 vcc, s0, v157
	s_and_b64 vcc, s[30:31], vcc
	v_max3_f32 v38, v38, v72, v73
	v_cndmask_b32_e32 v94, v198, v108, vcc
	v_cmp_le_i32_e32 vcc, s0, v157
	s_and_b64 vcc, s[34:35], vcc
	v_max3_f32 v38, v38, v74, v75
	v_cndmask_b32_e32 v95, v198, v109, vcc
	v_cmp_lt_i32_e32 vcc, s0, v158
	s_and_b64 vcc, s[36:37], vcc
	v_max3_f32 v38, v38, v94, v95
	v_cndmask_b32_e32 v96, v198, v110, vcc
	v_cmp_lt_i32_e32 vcc, s0, v159
	s_and_b64 vcc, s[38:39], vcc
	v_cndmask_b32_e64 v76, v198, v76, s[72:73]
	v_cndmask_b32_e32 v97, v198, v111, vcc
	v_cmp_lt_i32_e32 vcc, s0, v160
	s_and_b64 vcc, s[40:41], vcc
	v_max3_f32 v38, v38, v96, v97
	v_cndmask_b32_e32 v98, v198, v104, vcc
	v_cmp_le_i32_e32 vcc, s0, v160
	s_and_b64 vcc, s[42:43], vcc
	v_cndmask_b32_e64 v77, v198, v77, s[74:75]
	v_cndmask_b32_e32 v99, v198, v105, vcc
	v_cmp_lt_i32_e32 vcc, s0, v161
	s_and_b64 vcc, s[44:45], vcc
	v_max3_f32 v38, v38, v98, v99
	v_cndmask_b32_e32 v104, v198, v106, vcc
	v_cmp_lt_i32_e32 vcc, s0, v162
	s_and_b64 vcc, s[46:47], vcc
	v_cndmask_b32_e64 v78, v198, v78, s[76:77]
	v_cndmask_b32_e32 v105, v198, v107, vcc
	v_cmp_lt_i32_e32 vcc, s0, v163
	s_and_b64 vcc, s[48:49], vcc
	v_max3_f32 v38, v38, v104, v105
	v_cndmask_b32_e32 v100, v198, v100, vcc
	v_cmp_le_i32_e32 vcc, s0, v163
	s_and_b64 vcc, s[50:51], vcc
	v_cndmask_b32_e64 v79, v198, v79, s[78:79]
	v_cndmask_b32_e32 v101, v198, v101, vcc
	v_cmp_lt_i32_e32 vcc, s0, v164
	s_and_b64 vcc, s[52:53], vcc
	v_max3_f32 v38, v38, v100, v101
	v_cndmask_b32_e32 v102, v198, v102, vcc
	v_cmp_lt_i32_e32 vcc, s0, v165
	s_and_b64 vcc, s[54:55], vcc
	s_nop 0
	v_cndmask_b32_e32 v103, v198, v103, vcc
	v_cmp_lt_i32_e32 vcc, s0, v166
	s_and_b64 vcc, s[56:57], vcc
	v_max3_f32 v38, v38, v102, v103
	v_cndmask_b32_e32 v84, v198, v84, vcc
	v_cmp_le_i32_e32 vcc, s0, v166
	s_and_b64 vcc, s[58:59], vcc
	s_nop 0
	v_cndmask_b32_e32 v85, v198, v85, vcc
	v_cmp_lt_i32_e32 vcc, s0, v167
	s_and_b64 vcc, s[60:61], vcc
	v_max3_f32 v38, v38, v84, v85
	v_cndmask_b32_e32 v86, v198, v86, vcc
	v_cmp_lt_i32_e32 vcc, s0, v168
	s_and_b64 vcc, s[62:63], vcc
	s_nop 0
	v_cndmask_b32_e32 v87, v198, v87, vcc
	v_cmp_lt_i32_e32 vcc, s0, v169
	s_and_b64 vcc, s[64:65], vcc
	v_max3_f32 v38, v38, v86, v87
	v_cndmask_b32_e32 v80, v198, v80, vcc
	v_cmp_le_i32_e32 vcc, s0, v169
	s_and_b64 vcc, s[66:67], vcc
	s_nop 0
	v_cndmask_b32_e32 v81, v198, v81, vcc
	v_cmp_lt_i32_e32 vcc, s0, v170
	s_and_b64 vcc, s[68:69], vcc
	v_max3_f32 v38, v38, v80, v81
	v_cndmask_b32_e32 v82, v198, v82, vcc
	v_cmp_lt_i32_e32 vcc, s0, v171
	s_and_b64 vcc, s[70:71], vcc
	v_cmp_lt_f32_e64 s[0:1], s85, v37
	v_cndmask_b32_e32 v83, v198, v83, vcc
	v_max3_f32 v38, v38, v82, v83
	v_max3_f32 v38, v38, v76, v77
	v_max3_f32 v38, v38, v78, v79
	v_mov_b32_e32 v106, v38
	s_nop 1
	v_permlane16_swap_b32 v106, v106
	s_nop 1
	s_cmp_gt_i32 s6, 1
	s_waitcnt lgkmcnt(0)
; __device__ __forceinline__ void p4_attn(const Params& p, LAS unsigned char* lds, const int dummy) {
;     ...
;         mx = fmaxf(mx, __shfl_xor(mx, 16)); mx = fmaxf(mx, __shfl_xor(mx, 32));
;         float lsum = 0.f;
; #pragma unroll
;         for (int i = 0; i < 9; ++i)
; #pragma unroll
;             for (int j = 0; j < 4; ++j) { const float pe = (sT[i][j] > -1e29f) ? exp2f(sT[i][j] - mx) : 0.f; sT[i][j] = pe; lsum += pe; }
;         lsum += __shfl_xor(lsum, 16); lsum += __shfl_xor(lsum, 32);
	v_max_f32_e32 v106, v106, v106
	v_max_f32_e32 v38, v38, v106
	v_mov_b32_e32 v106, v38
	s_nop 1
	v_permlane32_swap_b32 v106, v106
	s_nop 1
	s_waitcnt lgkmcnt(0)
	v_max_f32_e32 v106, v106, v106
	v_max_f32_e32 v38, v38, v106
	v_sub_f32_e32 v106, v37, v38
	v_cmp_gt_f32_e32 vcc, s33, v106
	s_nop 1
	v_cndmask_b32_e32 v107, 0, v199, vcc
	v_add_f32_e32 v106, v106, v107
	v_exp_f32_e32 v106, v106
	v_cndmask_b32_e32 v107, 0, v200, vcc
	v_ldexp_f32 v106, v106, v107
	v_sub_f32_e32 v107, v39, v38
	v_cmp_gt_f32_e32 vcc, s33, v107
	v_cndmask_b32_e64 v209, 0, v106, s[0:1]
	v_sub_f32_e32 v106, v92, v38
	v_cndmask_b32_e32 v108, 0, v199, vcc
	v_add_f32_e32 v107, v107, v108
	v_exp_f32_e32 v107, v107
	v_cndmask_b32_e32 v37, 0, v200, vcc
	v_cmp_gt_f32_e32 vcc, s33, v106
	v_cmp_lt_f32_e64 s[0:1], s85, v39
	v_ldexp_f32 v37, v107, v37
	v_cndmask_b32_e32 v107, 0, v199, vcc
	v_add_f32_e32 v106, v106, v107
	v_exp_f32_e32 v106, v106
	v_cndmask_b32_e32 v39, 0, v200, vcc
	v_cndmask_b32_e64 v210, 0, v37, s[0:1]
	v_cmp_lt_f32_e64 s[0:1], s85, v92
	v_ldexp_f32 v39, v106, v39
	v_sub_f32_e32 v106, v93, v38
	v_cmp_gt_f32_e32 vcc, s33, v106
	v_sub_f32_e32 v92, v88, v38
	v_cndmask_b32_e64 v213, 0, v39, s[0:1]
	v_cndmask_b32_e32 v107, 0, v199, vcc
	v_add_f32_e32 v106, v106, v107
	v_exp_f32_e32 v106, v106
	v_cndmask_b32_e32 v39, 0, v200, vcc
	v_cmp_gt_f32_e32 vcc, s33, v92
	v_cmp_lt_f32_e64 s[0:1], s85, v93
	v_ldexp_f32 v39, v106, v39
	v_cndmask_b32_e32 v106, 0, v199, vcc
	v_add_f32_e32 v92, v92, v106
	v_exp_f32_e32 v92, v92
	v_cndmask_b32_e64 v215, 0, v39, s[0:1]
	v_cndmask_b32_e32 v39, 0, v200, vcc
	v_cmp_lt_f32_e64 s[0:1], s85, v88
	v_ldexp_f32 v39, v92, v39
	v_sub_f32_e32 v92, v89, v38
	v_cmp_gt_f32_e32 vcc, s33, v92
	v_sub_f32_e32 v88, v90, v38
	v_cndmask_b32_e64 v217, 0, v39, s[0:1]
	v_cndmask_b32_e32 v93, 0, v199, vcc
	v_add_f32_e32 v92, v92, v93
	v_exp_f32_e32 v92, v92
	v_cndmask_b32_e32 v39, 0, v200, vcc
	v_cmp_gt_f32_e32 vcc, s33, v88
	v_cmp_lt_f32_e64 s[0:1], s85, v89
	v_ldexp_f32 v39, v92, v39
	v_cndmask_b32_e32 v92, 0, v199, vcc
	v_add_f32_e32 v88, v88, v92
	v_exp_f32_e32 v88, v88
	v_cndmask_b32_e64 v218, 0, v39, s[0:1]
	v_cndmask_b32_e32 v39, 0, v200, vcc
	v_cmp_lt_f32_e64 s[0:1], s85, v90
	v_ldexp_f32 v39, v88, v39
	v_sub_f32_e32 v88, v91, v38
	v_cmp_gt_f32_e32 vcc, s33, v88
	v_cndmask_b32_e64 v219, 0, v39, s[0:1]
	v_cmp_lt_f32_e64 s[0:1], s85, v91
	v_cndmask_b32_e32 v89, 0, v199, vcc
	v_add_f32_e32 v88, v88, v89
	v_exp_f32_e32 v88, v88
	v_cndmask_b32_e32 v39, 0, v200, vcc
	v_add_f32_e32 v37, v209, v210
	v_add_f32_e32 v37, v213, v37
	v_ldexp_f32 v39, v88, v39
	v_sub_f32_e32 v88, v72, v38
	v_cmp_gt_f32_e32 vcc, s33, v88
	v_cndmask_b32_e64 v220, 0, v39, s[0:1]
	v_cmp_lt_f32_e64 s[0:1], s85, v72
	v_cndmask_b32_e32 v89, 0, v199, vcc
	v_add_f32_e32 v88, v88, v89
	v_exp_f32_e32 v88, v88
	v_cndmask_b32_e32 v39, 0, v200, vcc
	v_sub_f32_e32 v72, v74, v38
	v_add_f32_e32 v37, v215, v37
	v_ldexp_f32 v39, v88, v39
	v_sub_f32_e32 v88, v73, v38
	v_cmp_gt_f32_e32 vcc, s33, v88
	v_cndmask_b32_e64 v201, 0, v39, s[0:1]
	v_cmp_lt_f32_e64 s[0:1], s85, v73
	v_cndmask_b32_e32 v89, 0, v199, vcc
	v_add_f32_e32 v88, v88, v89
	v_exp_f32_e32 v88, v88
	v_cndmask_b32_e32 v39, 0, v200, vcc
	v_cmp_gt_f32_e32 vcc, s33, v72
	v_add_f32_e32 v37, v217, v37
	v_ldexp_f32 v39, v88, v39
	v_cndmask_b32_e32 v88, 0, v199, vcc
	v_add_f32_e32 v72, v72, v88
	v_exp_f32_e32 v72, v72
	v_cndmask_b32_e64 v203, 0, v39, s[0:1]
	v_cndmask_b32_e32 v39, 0, v200, vcc
	v_cmp_lt_f32_e64 s[0:1], s85, v74
	v_ldexp_f32 v39, v72, v39
	v_sub_f32_e32 v72, v75, v38
	v_cmp_gt_f32_e32 vcc, s33, v72
	v_cndmask_b32_e64 v205, 0, v39, s[0:1]
	v_cmp_lt_f32_e64 s[0:1], s85, v75
	v_cndmask_b32_e32 v73, 0, v199, vcc
	v_add_f32_e32 v72, v72, v73
	v_exp_f32_e32 v72, v72
	v_cndmask_b32_e32 v39, 0, v200, vcc
	v_add_f32_e32 v37, v218, v37
	v_add_f32_e32 v37, v219, v37
	v_ldexp_f32 v39, v72, v39
	v_sub_f32_e32 v72, v94, v38
	v_cmp_gt_f32_e32 vcc, s33, v72
	v_cndmask_b32_e64 v207, 0, v39, s[0:1]
	v_cmp_lt_f32_e64 s[0:1], s85, v94
	v_cndmask_b32_e32 v73, 0, v199, vcc
	v_add_f32_e32 v72, v72, v73
	v_exp_f32_e32 v72, v72
	v_cndmask_b32_e32 v39, 0, v200, vcc
	v_add_f32_e32 v37, v220, v37
	v_add_f32_e32 v37, v201, v37
	v_ldexp_f32 v39, v72, v39
	v_sub_f32_e32 v72, v95, v38
	v_cmp_gt_f32_e32 vcc, s33, v72
	v_cndmask_b32_e64 v208, 0, v39, s[0:1]
	v_cmp_lt_f32_e64 s[0:1], s85, v95
	v_cndmask_b32_e32 v73, 0, v199, vcc
	v_add_f32_e32 v72, v72, v73
	v_exp_f32_e32 v72, v72
	v_cndmask_b32_e32 v39, 0, v200, vcc
	v_add_f32_e32 v37, v203, v37
	v_add_f32_e32 v37, v205, v37
	v_ldexp_f32 v39, v72, v39
	v_sub_f32_e32 v72, v96, v38
	v_cmp_gt_f32_e32 vcc, s33, v72
	v_cndmask_b32_e64 v211, 0, v39, s[0:1]
	v_cmp_lt_f32_e64 s[0:1], s85, v96
	v_cndmask_b32_e32 v73, 0, v199, vcc
	v_add_f32_e32 v72, v72, v73
	v_exp_f32_e32 v72, v72
	v_cndmask_b32_e32 v39, 0, v200, vcc
	v_add_f32_e32 v37, v207, v37
	v_add_f32_e32 v37, v208, v37
	v_ldexp_f32 v39, v72, v39
	v_sub_f32_e32 v72, v97, v38
	v_cmp_gt_f32_e32 vcc, s33, v72
	v_cndmask_b32_e64 v214, 0, v39, s[0:1]
	v_cmp_lt_f32_e64 s[0:1], s85, v97
	v_cndmask_b32_e32 v73, 0, v199, vcc
	v_add_f32_e32 v72, v72, v73
	v_exp_f32_e32 v72, v72
	v_cndmask_b32_e32 v39, 0, v200, vcc
	v_add_f32_e32 v37, v211, v37
	v_add_f32_e32 v37, v214, v37
	v_ldexp_f32 v39, v72, v39
	v_sub_f32_e32 v72, v98, v38
	v_cmp_gt_f32_e32 vcc, s33, v72
	v_cndmask_b32_e64 v216, 0, v39, s[0:1]
	v_cmp_lt_f32_e64 s[0:1], s85, v98
	v_cndmask_b32_e32 v73, 0, v199, vcc
	v_add_f32_e32 v72, v72, v73
	v_exp_f32_e32 v72, v72
	v_cndmask_b32_e32 v39, 0, v200, vcc
	v_add_f32_e32 v37, v216, v37
	v_mov_b64_e32 v[90:91], s[82:83]
	v_ldexp_f32 v39, v72, v39
	v_sub_f32_e32 v72, v99, v38
; __device__ __forceinline__ void p4_attn(const Params& p, LAS unsigned char* lds, const int dummy) {
;     ...
; #pragma unroll
;         for (int i = 0; i < 9; ++i)
; #pragma unroll
;             for (int j = 0; j < 4; ++j) { const float pe = (sT[i][j] > -1e29f) ? exp2f(sT[i][j] - mx) : 0.f; sT[i][j] = pe; lsum += pe; }
;         lsum += __shfl_xor(lsum, 16); lsum += __shfl_xor(lsum, 32);
;         f32x4 oacc[8];
; #pragma unroll
;         for (int et = 0; et < 8; ++et) oacc[et] = (f32x4){0.f, 0.f, 0.f, 0.f};
	v_cmp_gt_f32_e32 vcc, s33, v72
	v_cndmask_b32_e64 v109, 0, v39, s[0:1]
	v_cmp_lt_f32_e64 s[0:1], s85, v99
	v_cndmask_b32_e32 v73, 0, v199, vcc
	v_add_f32_e32 v72, v72, v73
	v_exp_f32_e32 v72, v72
	v_cndmask_b32_e32 v39, 0, v200, vcc
	v_add_f32_e32 v37, v109, v37
	v_mov_b64_e32 v[94:95], s[82:83]
	v_ldexp_f32 v39, v72, v39
	v_sub_f32_e32 v72, v104, v38
	v_cmp_gt_f32_e32 vcc, s33, v72
	v_cndmask_b32_e64 v111, 0, v39, s[0:1]
	v_cmp_lt_f32_e64 s[0:1], s85, v104
	v_cndmask_b32_e32 v73, 0, v199, vcc
	v_add_f32_e32 v72, v72, v73
	v_exp_f32_e32 v72, v72
	v_cndmask_b32_e32 v39, 0, v200, vcc
	v_add_f32_e32 v37, v111, v37
	v_mov_b64_e32 v[98:99], s[82:83]
	v_ldexp_f32 v39, v72, v39
	v_sub_f32_e32 v72, v105, v38
	v_cmp_gt_f32_e32 vcc, s33, v72
	v_cndmask_b32_e64 v123, 0, v39, s[0:1]
	v_cmp_lt_f32_e64 s[0:1], s85, v105
	v_cndmask_b32_e32 v73, 0, v199, vcc
	v_add_f32_e32 v72, v72, v73
	v_exp_f32_e32 v72, v72
	v_cndmask_b32_e32 v39, 0, v200, vcc
	v_add_f32_e32 v37, v123, v37
	v_mov_b64_e32 v[88:89], s[80:81]
	v_ldexp_f32 v39, v72, v39
	v_sub_f32_e32 v72, v100, v38
	v_cmp_gt_f32_e32 vcc, s33, v72
	v_cndmask_b32_e64 v128, 0, v39, s[0:1]
	v_cmp_lt_f32_e64 s[0:1], s85, v100
	v_cndmask_b32_e32 v73, 0, v199, vcc
	v_add_f32_e32 v72, v72, v73
	v_exp_f32_e32 v72, v72
	v_cndmask_b32_e32 v39, 0, v200, vcc
	v_add_f32_e32 v37, v128, v37
	v_mov_b64_e32 v[92:93], s[80:81]
	v_ldexp_f32 v39, v72, v39
	v_sub_f32_e32 v72, v101, v38
	v_cmp_gt_f32_e32 vcc, s33, v72
	v_cndmask_b32_e64 v129, 0, v39, s[0:1]
	v_cmp_lt_f32_e64 s[0:1], s85, v101
	v_cndmask_b32_e32 v73, 0, v199, vcc
	v_add_f32_e32 v72, v72, v73
	v_exp_f32_e32 v72, v72
	v_cndmask_b32_e32 v39, 0, v200, vcc
	v_add_f32_e32 v37, v129, v37
	v_mov_b64_e32 v[96:97], s[80:81]
	v_ldexp_f32 v39, v72, v39
	v_sub_f32_e32 v72, v102, v38
	v_cmp_gt_f32_e32 vcc, s33, v72
	v_cndmask_b32_e64 v202, 0, v39, s[0:1]
	v_cmp_lt_f32_e64 s[0:1], s85, v102
	v_cndmask_b32_e32 v73, 0, v199, vcc
	v_add_f32_e32 v72, v72, v73
	v_exp_f32_e32 v72, v72
	v_cndmask_b32_e32 v39, 0, v200, vcc
	v_add_f32_e32 v37, v202, v37
	v_ldexp_f32 v39, v72, v39
	v_sub_f32_e32 v72, v103, v38
	v_cmp_gt_f32_e32 vcc, s33, v72
	v_cndmask_b32_e64 v204, 0, v39, s[0:1]
	v_cmp_lt_f32_e64 s[0:1], s85, v103
	v_cndmask_b32_e32 v73, 0, v199, vcc
	v_add_f32_e32 v72, v72, v73
	v_exp_f32_e32 v72, v72
	v_cndmask_b32_e32 v39, 0, v200, vcc
	v_add_f32_e32 v37, v204, v37
	v_ldexp_f32 v39, v72, v39
	v_sub_f32_e32 v72, v84, v38
	v_cmp_gt_f32_e32 vcc, s33, v72
	v_cndmask_b32_e64 v206, 0, v39, s[0:1]
	v_cmp_lt_f32_e64 s[0:1], s85, v84
	v_cndmask_b32_e32 v73, 0, v199, vcc
	v_add_f32_e32 v72, v72, v73
	v_exp_f32_e32 v72, v72
	v_cndmask_b32_e32 v39, 0, v200, vcc
	v_add_f32_e32 v37, v206, v37
	v_ldexp_f32 v39, v72, v39
	v_sub_f32_e32 v72, v85, v38
	v_cmp_gt_f32_e32 vcc, s33, v72
	v_cndmask_b32_e64 v104, 0, v39, s[0:1]
	v_cmp_lt_f32_e64 s[0:1], s85, v85
	v_cndmask_b32_e32 v73, 0, v199, vcc
	v_add_f32_e32 v72, v72, v73
	v_exp_f32_e32 v72, v72
	v_cndmask_b32_e32 v39, 0, v200, vcc
	v_add_f32_e32 v37, v104, v37
	v_ldexp_f32 v39, v72, v39
	v_sub_f32_e32 v72, v86, v38
	v_cmp_gt_f32_e32 vcc, s33, v72
	v_cndmask_b32_e64 v105, 0, v39, s[0:1]
	v_cmp_lt_f32_e64 s[0:1], s85, v86
	v_cndmask_b32_e32 v73, 0, v199, vcc
	v_add_f32_e32 v72, v72, v73
	v_exp_f32_e32 v72, v72
	v_cndmask_b32_e32 v39, 0, v200, vcc
	v_add_f32_e32 v37, v105, v37
	v_ldexp_f32 v39, v72, v39
	v_sub_f32_e32 v72, v87, v38
	v_cmp_gt_f32_e32 vcc, s33, v72
	v_cndmask_b32_e64 v106, 0, v39, s[0:1]
	v_cmp_lt_f32_e64 s[0:1], s85, v87
	v_cndmask_b32_e32 v73, 0, v199, vcc
	v_add_f32_e32 v72, v72, v73
	v_exp_f32_e32 v72, v72
	v_cndmask_b32_e32 v39, 0, v200, vcc
	v_add_f32_e32 v37, v106, v37
	v_mov_b64_e32 v[86:87], s[82:83]
	v_ldexp_f32 v39, v72, v39
	v_sub_f32_e32 v72, v80, v38
	v_cmp_gt_f32_e32 vcc, s33, v72
	v_cndmask_b32_e64 v107, 0, v39, s[0:1]
	v_cmp_lt_f32_e64 s[0:1], s85, v80
	v_cndmask_b32_e32 v73, 0, v199, vcc
	v_add_f32_e32 v72, v72, v73
	v_exp_f32_e32 v72, v72
	v_cndmask_b32_e32 v39, 0, v200, vcc
	v_add_f32_e32 v37, v107, v37
	v_mov_b64_e32 v[84:85], s[80:81]
	v_ldexp_f32 v39, v72, v39
	v_sub_f32_e32 v72, v81, v38
	v_cmp_gt_f32_e32 vcc, s33, v72
	v_cndmask_b32_e64 v108, 0, v39, s[0:1]
	v_cmp_lt_f32_e64 s[0:1], s85, v81
	v_cndmask_b32_e32 v73, 0, v199, vcc
	v_add_f32_e32 v72, v72, v73
	v_exp_f32_e32 v72, v72
	v_cndmask_b32_e32 v39, 0, v200, vcc
	v_add_f32_e32 v37, v108, v37
	v_ldexp_f32 v39, v72, v39
	v_sub_f32_e32 v72, v82, v38
	v_cmp_gt_f32_e32 vcc, s33, v72
	v_cndmask_b32_e64 v110, 0, v39, s[0:1]
	v_cmp_lt_f32_e64 s[0:1], s85, v82
	v_cndmask_b32_e32 v73, 0, v199, vcc
	v_add_f32_e32 v72, v72, v73
	v_exp_f32_e32 v72, v72
	v_cndmask_b32_e32 v39, 0, v200, vcc
	v_add_f32_e32 v37, v110, v37
	v_ldexp_f32 v39, v72, v39
	v_sub_f32_e32 v72, v83, v38
	v_cmp_gt_f32_e32 vcc, s33, v72
	v_cndmask_b32_e64 v121, 0, v39, s[0:1]
	v_cmp_lt_f32_e64 s[0:1], s85, v83
	v_cndmask_b32_e32 v73, 0, v199, vcc
	v_add_f32_e32 v72, v72, v73
	v_exp_f32_e32 v72, v72
	v_cndmask_b32_e32 v39, 0, v200, vcc
	v_add_f32_e32 v37, v121, v37
	v_mov_b64_e32 v[80:81], s[80:81]
	v_ldexp_f32 v39, v72, v39
	v_sub_f32_e32 v72, v76, v38
	v_cmp_gt_f32_e32 vcc, s33, v72
	v_cndmask_b32_e64 v125, 0, v39, s[0:1]
	v_cmp_lt_f32_e64 s[0:1], s85, v76
	v_cndmask_b32_e32 v73, 0, v199, vcc
	v_add_f32_e32 v72, v72, v73
	v_exp_f32_e32 v72, v72
	v_cndmask_b32_e32 v39, 0, v200, vcc
	v_add_f32_e32 v37, v125, v37
	v_mov_b64_e32 v[82:83], s[82:83]
	v_ldexp_f32 v39, v72, v39
	v_sub_f32_e32 v72, v77, v38
	v_cmp_gt_f32_e32 vcc, s33, v72
	v_cndmask_b32_e64 v100, 0, v39, s[0:1]
	v_cmp_lt_f32_e64 s[0:1], s85, v77
	v_cndmask_b32_e32 v73, 0, v199, vcc
	v_add_f32_e32 v72, v72, v73
	v_exp_f32_e32 v72, v72
	v_cndmask_b32_e32 v39, 0, v200, vcc
	v_add_f32_e32 v37, v100, v37
	v_ldexp_f32 v39, v72, v39
	v_sub_f32_e32 v72, v78, v38
	v_cmp_gt_f32_e32 vcc, s33, v72
	v_cndmask_b32_e64 v101, 0, v39, s[0:1]
	v_cmp_lt_f32_e64 s[0:1], s85, v78
	v_cndmask_b32_e32 v73, 0, v199, vcc
	v_add_f32_e32 v72, v72, v73
	v_exp_f32_e32 v72, v72
	v_cndmask_b32_e32 v39, 0, v200, vcc
	v_add_f32_e32 v37, v101, v37
	v_ldexp_f32 v39, v72, v39
	v_sub_f32_e32 v72, v79, v38
	v_cmp_gt_f32_e32 vcc, s33, v72
	v_cndmask_b32_e64 v102, 0, v39, s[0:1]
	v_add_f32_e32 v37, v102, v37
	v_cndmask_b32_e32 v73, 0, v199, vcc
	v_add_f32_e32 v72, v72, v73
	v_exp_f32_e32 v72, v72
	v_cndmask_b32_e32 v39, 0, v200, vcc
	v_cmp_lt_f32_e32 vcc, s85, v79
	v_mov_b64_e32 v[76:77], s[80:81]
	v_ldexp_f32 v39, v72, v39
	v_cndmask_b32_e32 v103, 0, v39, vcc
	v_add_f32_e32 v37, v103, v37
	v_mov_b32_e32 v39, v37
	s_nop 1
	v_permlane16_swap_b32 v39, v39
	s_nop 1
	v_mov_b64_e32 v[72:73], s[80:81]
	v_mov_b64_e32 v[74:75], s[82:83]
	v_mov_b64_e32 v[78:79], s[82:83]
	s_waitcnt lgkmcnt(0)
	v_add_f32_e32 v37, v37, v39
	v_mov_b32_e32 v39, v37
	s_nop 1
	v_permlane32_swap_b32 v39, v39
	s_nop 1
	s_cbranch_scc1 .LBB0_622
; __device__ __forceinline__ unsigned cvt_pk_bf16(float lo, float hi) { const f32x2_t f = {lo, hi}; const bf16x2_t b = __builtin_convertvector(f, bf16x2_t); return __builtin_bit_cast(unsigned, b); }
; __device__ __forceinline__ u32x2 tr_read(LAS unsigned char* addr) { const s16x4 v = __builtin_amdgcn_ds_read_tr16_b64_v4i16((LAS s16x4*)addr); return __builtin_bit_cast(u32x2, v); }
; __device__ __forceinline__ void p4_attn(const Params& p, LAS unsigned char* lds, const int dummy) {
;     ...
;         for (int ps = 0; ps < 5; ++ps) {
;             if (2 * ps + 1 >= ilo) {
;                 u32x4 bw; bw.x = cvt_pk_bf16(sT[2 * ps][0], sT[2 * ps][1]); bw.y = cvt_pk_bf16(sT[2 * ps][2], sT[2 * ps][3]);
;                 if (ps < 4) { bw.z = cvt_pk_bf16(sT[(2 * ps + 1) % 9][0], sT[(2 * ps + 1) % 9][1]); bw.w = cvt_pk_bf16(sT[(2 * ps + 1) % 9][2], sT[(2 * ps + 1) % 9][3]); } else { bw.z = 0u; bw.w = 0u; }
;                 const bf16x8 bfrag = __builtin_bit_cast(bf16x8, bw);
;                 u32x2 vlo[8], vhi[8];
; #pragma unroll
;                 for (int et = 0; et < 8; ++et) {
;                     vlo[et] = tr_read(VB + (16 * (wid + 2 * ps) + 4 * q + (r >> 2)) * VB_STRIDE + (16 * et + 4 * (r & 3)) * 2);
;                     vhi[et] = (u32x2){0u, 0u};
;                     if (ps < 4) vhi[et] = tr_read(VB + (16 * (wid + 2 * ps + 1) + 4 * q + (r >> 2)) * VB_STRIDE + (16 * et + 4 * (r & 3)) * 2);
;                 }
;                 __builtin_amdgcn_sched_barrier(0);
; #pragma unroll
;                 for (int et = 0; et < 8; ++et) {
;                     u32x4 aw; aw.x = vlo[et].x; aw.y = vlo[et].y; aw.z = vhi[et].x; aw.w = vhi[et].y;
;                     oacc[et] = __builtin_amdgcn_mfma_f32_16x16x32_bf16(__builtin_bit_cast(bf16x8, aw), bfrag, oacc[et], 0, 0, 0);
;                 }
;                 __builtin_amdgcn_sched_barrier(0);
	v_cvt_pk_bf16_f32 v70, v217, v218
	v_cvt_pk_bf16_f32 v71, v219, v220
	ds_read_b64_tr_b16 v[72:73], v189
	ds_read_b64_tr_b16 v[76:77], v189 offset:32
	ds_read_b64_tr_b16 v[74:75], v190
	ds_read_b64_tr_b16 v[78:79], v190 offset:32
	ds_read_b64_tr_b16 v[80:81], v189 offset:64
	ds_read_b64_tr_b16 v[82:83], v190 offset:64
	ds_read_b64_tr_b16 v[84:85], v189 offset:96
	ds_read_b64_tr_b16 v[86:87], v190 offset:96
	ds_read_b64_tr_b16 v[218:219], v189 offset:128
	ds_read_b64_tr_b16 v[220:221], v190 offset:128
	ds_read_b64_tr_b16 v[222:223], v189 offset:160
	ds_read_b64_tr_b16 v[224:225], v190 offset:160
	ds_read_b64_tr_b16 v[226:227], v189 offset:192
	ds_read_b64_tr_b16 v[228:229], v190 offset:192
	ds_read_b64_tr_b16 v[230:231], v189 offset:224
	ds_read_b64_tr_b16 v[232:233], v190 offset:224
	v_cvt_pk_bf16_f32 v68, v209, v210
	v_cvt_pk_bf16_f32 v69, v213, v215
	s_waitcnt lgkmcnt(13)
	s_nop 0
	v_mfma_f32_16x16x32_bf16 v[96:99], v[72:75], v[68:71], 0
	s_waitcnt lgkmcnt(12)
	v_mfma_f32_16x16x32_bf16 v[92:95], v[76:79], v[68:71], 0
	s_waitcnt lgkmcnt(10)
	v_mfma_f32_16x16x32_bf16 v[88:91], v[80:83], v[68:71], 0
	s_waitcnt lgkmcnt(8)
	v_mfma_f32_16x16x32_bf16 v[84:87], v[84:87], v[68:71], 0
	s_waitcnt lgkmcnt(6)
	v_mfma_f32_16x16x32_bf16 v[80:83], v[218:221], v[68:71], 0
	s_waitcnt lgkmcnt(4)
	v_mfma_f32_16x16x32_bf16 v[76:79], v[222:225], v[68:71], 0
	s_waitcnt lgkmcnt(2)
	v_mfma_f32_16x16x32_bf16 v[72:75], v[226:229], v[68:71], 0
	s_waitcnt lgkmcnt(0)
	v_mfma_f32_16x16x32_bf16 v[68:71], v[230:233], v[68:71], 0
	s_cmp_gt_i32 s6, 3
	s_cbranch_scc0 .LBB0_623

;     __device__ __forceinline__ void fused(f32x4 (&acc)[2][2][4][2], const pg8::Unit& u, int wr, int wc, int fr, int fq, LAS unsigned char* lds, int wid, int lane) const {
;     ...
;         const size_t off0 = (size_t)(u.pm * 256 + wr * 64 + fr) * 1024 + col0;
;         f32x4 xv[4][2][2];
; #pragma unroll
;         for (int m = 0; m < 4; ++m)
; #pragma unroll
;             for (int bj = 0; bj < 2; ++bj) { xv[m][bj][0] = __builtin_nontemporal_load((const f32x4*)(x + off0 + (size_t)(m * 16) * 1024 + bj * 128)); xv[m][bj][1] = __builtin_nontemporal_load((const f32x4*)(x + off0 + (size_t)(m * 16) * 1024 + bj * 128 + 4)); }
; #pragma unroll
;         for (int ai = 0; ai < 2; ++ai)
; #pragma unroll
;             for (int m = 0; m < 4; ++m) {
;                 float sq = 0.f;
; #pragma unroll
;                 for (int bj = 0; bj < 2; ++bj)
; #pragma unroll
;                     for (int n = 0; n < 2; ++n) { const f32x4 v = acc[ai][bj][m][n]; sq += (v[0] * v[0] + v[1] * v[1]) + (v[2] * v[2] + v[3] * v[3]); }
;                 sq += __shfl_xor(sq, 16); sq += __shfl_xor(sq, 32);
;                 if (fq == 0) P[(ai * 128 + wr * 64 + m * 16 + fr) * 4 + wc] = sq;
;             }
.LBB0_876:
	s_lshl_b32 s2, s9, 5
	s_lshl_b32 s3, s10, 8
	s_or_b32 s2, s3, s2
	v_lshl_or_b32 v192, v197, 3, s2
	s_lshl_b32 s2, s8, 8
	s_add_i32 s2, s2, s34
	v_or_b32_e32 v128, s2, v213
	v_ashrrev_i32_e32 v129, 31, v128
	v_lshlrev_b64 v[128:129], 10, v[128:129]
	v_ashrrev_i32_e32 v193, 31, v192
	v_readlane_b32 s12, v254, 4
	v_lshl_add_u64 v[210:211], v[128:129], 0, v[192:193]
	v_readlane_b32 s13, v254, 5
	s_mov_b64 s[2:3], 0x10000
	s_barrier
	v_lshl_add_u64 v[208:209], v[210:211], 2, s[12:13]
	v_lshl_add_u64 v[128:129], v[208:209], 0, s[2:3]
	s_mov_b32 s2, 0x10000
	v_add_co_u32_e32 v130, vcc, s2, v208
	s_mov_b64 s[2:3], 0x10200
	s_nop 0
	v_addc_co_u32_e32 v131, vcc, 0, v209, vcc
	global_load_dwordx4 v[152:155], v[208:209], off offset:16 nt
	global_load_dwordx4 v[160:163], v[208:209], off nt
	global_load_dwordx4 v[148:151], v[208:209], off offset:528 nt
	global_load_dwordx4 v[156:159], v[208:209], off offset:512 nt
	global_load_dwordx4 v[176:179], v[130:131], off nt
	global_load_dwordx4 v[164:167], v[128:129], off offset:16 nt
	v_lshl_add_u64 v[128:129], v[208:209], 0, s[2:3]
	s_mov_b64 s[2:3], 0x20000
	global_load_dwordx4 v[172:175], v[130:131], off offset:512 nt
	global_load_dwordx4 v[168:171], v[128:129], off offset:16 nt
	v_lshl_add_u64 v[128:129], v[208:209], 0, s[2:3]
	s_mov_b32 s2, 0x20000
	v_add_co_u32_e32 v130, vcc, s2, v208
	s_mov_b64 s[2:3], 0x20200
	s_nop 0
	v_addc_co_u32_e32 v131, vcc, 0, v209, vcc
	global_load_dwordx4 v[188:191], v[130:131], off nt
	global_load_dwordx4 v[180:183], v[128:129], off offset:16 nt
	v_lshl_add_u64 v[128:129], v[208:209], 0, s[2:3]
	s_mov_b64 s[2:3], 0x30000
	global_load_dwordx4 v[184:187], v[130:131], off offset:512 nt
	global_load_dwordx4 v[144:147], v[128:129], off offset:16 nt
	v_lshl_add_u64 v[128:129], v[208:209], 0, s[2:3]
	s_mov_b32 s2, 0x30000
	v_add_co_u32_e32 v130, vcc, s2, v208
	s_mov_b64 s[2:3], 0x30200
	s_nop 0
	v_addc_co_u32_e32 v131, vcc, 0, v209, vcc
	global_load_dwordx4 v[140:143], v[130:131], off nt
	global_load_dwordx4 v[136:139], v[128:129], off offset:16 nt
	v_lshl_add_u64 v[128:129], v[208:209], 0, s[2:3]
	global_load_dwordx4 v[132:135], v[130:131], off offset:512 nt
	s_nop 0
	global_load_dwordx4 v[128:131], v[128:129], off offset:16 nt
	v_mul_f32_e32 v201, v125, v125
	v_mul_f32_e32 v202, v127, v127
	v_fmac_f32_e32 v201, v124, v124
	v_fmac_f32_e32 v202, v126, v126
	v_add_f32_e32 v201, v201, v202
	v_mul_f32_e32 v202, v121, v121
	v_mul_f32_e32 v203, v123, v123
	v_fmac_f32_e32 v202, v120, v120
	v_fmac_f32_e32 v203, v122, v122
	v_add_f32_e32 v202, v202, v203
	v_mbcnt_lo_u32_b32 v198, -1, 0
	v_add_f32_e32 v201, v202, v201
	v_mul_f32_e32 v202, v109, v109
	v_mul_f32_e32 v203, v111, v111
	v_mbcnt_hi_u32_b32 v199, -1, v198
	v_fmac_f32_e32 v202, v108, v108
	v_fmac_f32_e32 v203, v110, v110
	v_and_b32_e32 v200, 64, v199
	v_add_f32_e32 v202, v202, v203
	v_xor_b32_e32 v198, 16, v199
	v_add_u32_e32 v200, 64, v200
	v_add_f32_e32 v201, v202, v201
	v_mul_f32_e32 v202, v105, v105
	v_mul_f32_e32 v203, v107, v107
	v_cmp_lt_i32_e32 vcc, v198, v200
	v_fmac_f32_e32 v202, v104, v104
	v_fmac_f32_e32 v203, v106, v106
	v_cndmask_b32_e32 v198, v199, v198, vcc
	v_add_f32_e32 v202, v202, v203
	v_lshlrev_b32_e32 v198, 2, v198
	v_add_f32_e32 v201, v202, v201
	v_mov_b32_e32 v202, v201
	s_nop 1
	v_permlane16_swap_b32 v202, v202
	s_nop 1
	v_xor_b32_e32 v203, 32, v199
	v_cmp_lt_i32_e32 vcc, v203, v200
	s_lshl_b32 s2, s9, 2
	s_add_i32 s2, s2, 0
	v_cndmask_b32_e32 v199, v199, v203, vcc
	v_lshlrev_b32_e32 v199, 2, v199
	s_waitcnt lgkmcnt(0)
	v_add_f32_e32 v200, v201, v202
	v_mov_b32_e32 v201, v200
	s_nop 1
	v_permlane32_swap_b32 v201, v201
	s_nop 1
	v_cmp_eq_u32_e32 vcc, 0, v197
	v_lshl_add_u32 v196, v196, 4, s2
	v_readlane_b32 s14, v254, 6
	v_readlane_b32 s15, v254, 7
	v_readlane_b32 s16, v254, 8
	v_readlane_b32 s17, v254, 9
	v_readlane_b32 s18, v254, 10
	v_readlane_b32 s19, v254, 11
	v_readlane_b32 s20, v254, 12
	v_readlane_b32 s21, v254, 13
	v_readlane_b32 s22, v254, 14
	v_readlane_b32 s23, v254, 15
	v_readlane_b32 s24, v254, 16
	v_readlane_b32 s25, v254, 17
	v_readlane_b32 s26, v254, 18
	v_readlane_b32 s27, v254, 19
	s_and_saveexec_b64 s[2:3], vcc
	s_cbranch_execz .LBB0_878
	s_waitcnt lgkmcnt(0)
	v_add_f32_e32 v197, v200, v201
	ds_write_b32 v196, v197
.LBB0_878:
	s_or_b64 exec, exec, s[2:3]
	v_mul_f32_e32 v197, v101, v101
	v_mul_f32_e32 v200, v103, v103
	v_fmac_f32_e32 v197, v100, v100
	v_fmac_f32_e32 v200, v102, v102
	v_add_f32_e32 v197, v197, v200
	v_mul_f32_e32 v200, v97, v97
	s_waitcnt lgkmcnt(0)
	v_mul_f32_e32 v201, v99, v99
	v_fmac_f32_e32 v200, v96, v96
	v_fmac_f32_e32 v201, v98, v98
	v_add_f32_e32 v200, v200, v201
	v_add_f32_e32 v197, v200, v197
	v_mul_f32_e32 v200, v89, v89
	v_mul_f32_e32 v201, v91, v91
	v_fmac_f32_e32 v200, v88, v88
	v_fmac_f32_e32 v201, v90, v90
	v_add_f32_e32 v200, v200, v201
	v_add_f32_e32 v197, v200, v197
	v_mul_f32_e32 v200, v85, v85
	v_mul_f32_e32 v201, v87, v87
	v_fmac_f32_e32 v200, v84, v84
	v_fmac_f32_e32 v201, v86, v86
	v_add_f32_e32 v200, v200, v201
	v_add_f32_e32 v197, v200, v197
	v_mov_b32_e32 v200, v197
	s_nop 1
	v_permlane16_swap_b32 v200, v200
	s_nop 1
	s_waitcnt lgkmcnt(0)
	v_add_f32_e32 v197, v197, v200
	v_mov_b32_e32 v200, v197
	s_nop 1
	v_permlane32_swap_b32 v200, v200
	s_nop 1
	s_and_saveexec_b64 s[2:3], vcc
	s_cbranch_execz .LBB0_880
	s_waitcnt lgkmcnt(0)
	v_add_f32_e32 v197, v197, v200
	ds_write_b32 v196, v197 offset:256
;     __device__ __forceinline__ void fused(f32x4 (&acc)[2][2][4][2], const pg8::Unit& u, int wr, int wc, int fr, int fq, LAS unsigned char* lds, int wid, int lane) const {
;     ...
;         for (int ai = 0; ai < 2; ++ai)
; #pragma unroll
;             for (int m = 0; m < 4; ++m) {
;                 float sq = 0.f;
; #pragma unroll
;                 for (int bj = 0; bj < 2; ++bj)
; #pragma unroll
;                     for (int n = 0; n < 2; ++n) { const f32x4 v = acc[ai][bj][m][n]; sq += (v[0] * v[0] + v[1] * v[1]) + (v[2] * v[2] + v[3] * v[3]); }
;                 sq += __shfl_xor(sq, 16); sq += __shfl_xor(sq, 32);
;                 if (fq == 0) P[(ai * 128 + wr * 64 + m * 16 + fr) * 4 + wc] = sq;
;             }
.LBB0_880:
	s_or_b64 exec, exec, s[2:3]
	v_mul_f32_e32 v197, v117, v117
	s_waitcnt lgkmcnt(0)
	v_mul_f32_e32 v200, v119, v119
	v_fmac_f32_e32 v197, v116, v116
	v_fmac_f32_e32 v200, v118, v118
	v_add_f32_e32 v197, v197, v200
	v_mul_f32_e32 v200, v113, v113
	v_mul_f32_e32 v201, v115, v115
	v_fmac_f32_e32 v200, v112, v112
	v_fmac_f32_e32 v201, v114, v114
	v_add_f32_e32 v200, v200, v201
	v_add_f32_e32 v197, v200, v197
	v_mul_f32_e32 v200, v93, v93
	v_mul_f32_e32 v201, v95, v95
	v_fmac_f32_e32 v200, v92, v92
	v_fmac_f32_e32 v201, v94, v94
	v_add_f32_e32 v200, v200, v201
	v_add_f32_e32 v197, v200, v197
	v_mul_f32_e32 v200, v81, v81
	v_mul_f32_e32 v201, v83, v83
	v_fmac_f32_e32 v200, v80, v80
	v_fmac_f32_e32 v201, v82, v82
	v_add_f32_e32 v200, v200, v201
	v_add_f32_e32 v197, v200, v197
	v_mov_b32_e32 v200, v197
	s_nop 1
	v_permlane16_swap_b32 v200, v200
	s_nop 1
	s_waitcnt lgkmcnt(0)
	v_add_f32_e32 v197, v197, v200
	v_mov_b32_e32 v200, v197
	s_nop 1
	v_permlane32_swap_b32 v200, v200
	s_nop 1
	s_and_saveexec_b64 s[2:3], vcc
	s_cbranch_execz .LBB0_882
	s_waitcnt lgkmcnt(0)
	v_add_f32_e32 v197, v197, v200
	ds_write_b32 v196, v197 offset:512
.LBB0_882:
	s_or_b64 exec, exec, s[2:3]
	v_mul_f32_e32 v197, v77, v77
	s_waitcnt lgkmcnt(0)
	v_mul_f32_e32 v200, v79, v79
	v_fmac_f32_e32 v197, v76, v76
	v_fmac_f32_e32 v200, v78, v78
	v_add_f32_e32 v197, v197, v200
	v_mul_f32_e32 v200, v73, v73
	v_mul_f32_e32 v201, v75, v75
	v_fmac_f32_e32 v200, v72, v72
	v_fmac_f32_e32 v201, v74, v74
	v_add_f32_e32 v200, v200, v201
	v_add_f32_e32 v197, v200, v197
	v_mul_f32_e32 v200, v69, v69
	v_mul_f32_e32 v201, v71, v71
	v_fmac_f32_e32 v200, v68, v68
	v_fmac_f32_e32 v201, v70, v70
	v_add_f32_e32 v200, v200, v201
	v_add_f32_e32 v197, v200, v197
	v_mul_f32_e32 v200, v65, v65
	v_mul_f32_e32 v201, v67, v67
	v_fmac_f32_e32 v200, v64, v64
	v_fmac_f32_e32 v201, v66, v66
	v_add_f32_e32 v200, v200, v201
	v_add_f32_e32 v197, v200, v197
	v_mov_b32_e32 v200, v197
	s_nop 1
	v_permlane16_swap_b32 v200, v200
	s_nop 1
	s_waitcnt lgkmcnt(0)
	v_add_f32_e32 v197, v197, v200
	v_mov_b32_e32 v200, v197
	s_nop 1
	v_permlane32_swap_b32 v200, v200
	s_nop 1
	s_and_saveexec_b64 s[2:3], vcc
	s_cbranch_execz .LBB0_884
	s_waitcnt lgkmcnt(0)
	v_add_f32_e32 v197, v197, v200
	ds_write_b32 v196, v197 offset:768
.LBB0_884:
	s_or_b64 exec, exec, s[2:3]
	v_mul_f32_e32 v197, v61, v61
	s_waitcnt lgkmcnt(0)
	v_mul_f32_e32 v200, v63, v63
	v_fmac_f32_e32 v197, v60, v60
	v_fmac_f32_e32 v200, v62, v62
	v_add_f32_e32 v197, v197, v200
	v_mul_f32_e32 v200, v57, v57
	v_mul_f32_e32 v201, v59, v59
	v_fmac_f32_e32 v200, v56, v56
	v_fmac_f32_e32 v201, v58, v58
	v_add_f32_e32 v200, v200, v201
	v_add_f32_e32 v197, v200, v197
	v_mul_f32_e32 v200, v49, v49
	v_mul_f32_e32 v201, v51, v51
	v_fmac_f32_e32 v200, v48, v48
	v_fmac_f32_e32 v201, v50, v50
	v_add_f32_e32 v200, v200, v201
	v_add_f32_e32 v197, v200, v197
	v_mul_f32_e32 v200, v45, v45
	v_mul_f32_e32 v201, v47, v47
	v_fmac_f32_e32 v200, v44, v44
	v_fmac_f32_e32 v201, v46, v46
	v_add_f32_e32 v200, v200, v201
	v_add_f32_e32 v197, v200, v197
	v_mov_b32_e32 v200, v197
	s_nop 1
	v_permlane16_swap_b32 v200, v200
	s_nop 1
	s_waitcnt lgkmcnt(0)
	v_add_f32_e32 v197, v197, v200
	v_mov_b32_e32 v200, v197
	s_nop 1
	v_permlane32_swap_b32 v200, v200
	s_nop 1
	s_and_saveexec_b64 s[2:3], vcc
	s_cbranch_execz .LBB0_886
	s_waitcnt lgkmcnt(0)
	v_add_f32_e32 v197, v197, v200
	ds_write_b32 v196, v197 offset:2048
.LBB0_886:
	s_or_b64 exec, exec, s[2:3]
	v_mul_f32_e32 v197, v53, v53
	s_waitcnt lgkmcnt(0)
	v_mul_f32_e32 v200, v55, v55
	v_fmac_f32_e32 v197, v52, v52
	v_fmac_f32_e32 v200, v54, v54
	v_add_f32_e32 v197, v197, v200
	v_mul_f32_e32 v200, v41, v41
	v_mul_f32_e32 v201, v43, v43
	v_fmac_f32_e32 v200, v40, v40
	v_fmac_f32_e32 v201, v42, v42
	v_add_f32_e32 v200, v200, v201
	v_add_f32_e32 v197, v200, v197
	v_mul_f32_e32 v200, v37, v37
	v_mul_f32_e32 v201, v39, v39
	v_fmac_f32_e32 v200, v36, v36
	v_fmac_f32_e32 v201, v38, v38
	v_add_f32_e32 v200, v200, v201
	v_add_f32_e32 v197, v200, v197
	v_mul_f32_e32 v200, v25, v25
	v_mul_f32_e32 v201, v27, v27
	v_fmac_f32_e32 v200, v24, v24
	v_fmac_f32_e32 v201, v26, v26
	v_add_f32_e32 v200, v200, v201
	v_add_f32_e32 v197, v200, v197
	v_mov_b32_e32 v200, v197
	s_nop 1
	v_permlane16_swap_b32 v200, v200
	s_nop 1
	s_waitcnt lgkmcnt(0)
	v_add_f32_e32 v197, v197, v200
	v_mov_b32_e32 v200, v197
	s_nop 1
	v_permlane32_swap_b32 v200, v200
	s_nop 1
	s_and_saveexec_b64 s[2:3], vcc
	s_cbranch_execz .LBB0_888
	s_waitcnt lgkmcnt(0)
	v_add_f32_e32 v197, v197, v200
	ds_write_b32 v196, v197 offset:2304
.LBB0_888:
	s_or_b64 exec, exec, s[2:3]
	v_mul_f32_e32 v197, v33, v33
	s_waitcnt lgkmcnt(0)
	v_mul_f32_e32 v200, v35, v35
	v_fmac_f32_e32 v197, v32, v32
	v_fmac_f32_e32 v200, v34, v34
	v_add_f32_e32 v197, v197, v200
	v_mul_f32_e32 v200, v29, v29
	v_mul_f32_e32 v201, v31, v31
	v_fmac_f32_e32 v200, v28, v28
	v_fmac_f32_e32 v201, v30, v30
	v_add_f32_e32 v200, v200, v201
	v_add_f32_e32 v197, v200, v197
	v_mul_f32_e32 v200, v17, v17
	v_mul_f32_e32 v201, v19, v19
	v_fmac_f32_e32 v200, v16, v16
	v_fmac_f32_e32 v201, v18, v18
	v_add_f32_e32 v200, v200, v201
	v_add_f32_e32 v197, v200, v197
	v_mul_f32_e32 v200, v13, v13
	v_mul_f32_e32 v201, v15, v15
	v_fmac_f32_e32 v200, v12, v12
	v_fmac_f32_e32 v201, v14, v14
	v_add_f32_e32 v200, v200, v201
	v_add_f32_e32 v197, v200, v197
	v_mov_b32_e32 v200, v197
	s_nop 1
	v_permlane16_swap_b32 v200, v200
	s_nop 1
	s_waitcnt lgkmcnt(0)
	v_add_f32_e32 v197, v197, v200
	v_mov_b32_e32 v200, v197
	s_nop 1
	v_permlane32_swap_b32 v200, v200
	s_nop 1
	s_and_saveexec_b64 s[2:3], vcc
	s_cbranch_execz .LBB0_890
	s_waitcnt lgkmcnt(0)
	v_add_f32_e32 v197, v197, v200
	ds_write_b32 v196, v197 offset:2560
.LBB0_890:
	s_or_b64 exec, exec, s[2:3]
	v_mul_f32_e32 v197, v21, v21
	s_waitcnt lgkmcnt(0)
	v_mul_f32_e32 v200, v23, v23
	v_fmac_f32_e32 v197, v20, v20
	v_fmac_f32_e32 v200, v22, v22
	v_add_f32_e32 v197, v197, v200
	v_mul_f32_e32 v200, v9, v9
	v_mul_f32_e32 v201, v11, v11
	v_fmac_f32_e32 v200, v8, v8
	v_fmac_f32_e32 v201, v10, v10
	v_add_f32_e32 v200, v200, v201
	v_add_f32_e32 v197, v200, v197
	v_mul_f32_e32 v200, v5, v5
	v_mul_f32_e32 v201, v7, v7
	v_fmac_f32_e32 v200, v4, v4
	v_fmac_f32_e32 v201, v6, v6
	v_add_f32_e32 v200, v200, v201
	v_add_f32_e32 v197, v200, v197
	v_mul_f32_e32 v200, v1, v1
	v_mul_f32_e32 v201, v3, v3
	v_fmac_f32_e32 v200, v0, v0
	v_fmac_f32_e32 v201, v2, v2
	v_add_f32_e32 v200, v200, v201
	v_add_f32_e32 v197, v200, v197
	v_mov_b32_e32 v198, v197
	s_nop 1
	v_permlane16_swap_b32 v198, v198
	s_nop 1
	s_waitcnt lgkmcnt(0)
	v_add_f32_e32 v197, v197, v198
	v_mov_b32_e32 v198, v197
	s_nop 1
	v_permlane32_swap_b32 v198, v198
	s_nop 1
	s_and_saveexec_b64 s[2:3], vcc
	s_cbranch_execz .LBB0_892
	s_waitcnt lgkmcnt(0)
	v_add_f32_e32 v197, v197, v198
	ds_write_b32 v196, v197 offset:2816
